# v34 + nt cache policy on the even-conv phase's bf16 input loads (read once; weights and biases keep the default policy)
# speedup vs baseline: 1.0072x; 1.0072x over previous
; template <int NT>
; __device__ __forceinline__ void even_conv_unit(const Params& p, LAS unsigned char* lds, int base, int T, int t0, int tid_in, int lane, int wave) {
;     ...
;     unsigned pv[NT + 2], bgv[NT], xr[NR];
; #pragma unroll
;     for (int i = 0; i < NT + 2; ++i) { const int tc = min(max(t0 - 1 + i, 0), T - 1); pv[i] = *(const unsigned*)(Z3 + (size_t)(base + tc) * ZE_LD + 1024 + 2 * tid); }
; #pragma unroll
;     for (int i = 0; i < NT; ++i) bgv[i] = *(const unsigned*)(Z3 + (size_t)(base + t0 + i) * ZE_LD + 2 * tid);
; #pragma unroll
;     for (int j = 0; j < NR; ++j) { const int tc = min(max(t0 - 15 + j, 0), T - 1); xr[j] = *(const unsigned*)(Z3 + (size_t)(base + tc) * ZE_LD + 2048 + 2 * tid); }
.LBB0_683:
	s_cmpk_gt_i32 s72, 0x1ff
	s_mov_b64 s[2:3], -1
	s_cbranch_scc0 .LBB0_729
	s_and_b32 s2, s74, 0x700
	s_add_i32 s2, s68, s2
	s_and_b32 s6, s72, 0xf8
	s_and_b32 s2, s2, 0x7fffff00
	s_add_i32 s7, s6, -1
	s_addk_i32 s2, 0x4000
	s_max_i32 s3, s7, 0
	v_mov_b32_e32 v146, v0
	s_or_b32 s3, s2, s3
	s_mulk_i32 s3, 0x1800
	s_waitcnt vmcnt(0)
	v_lshlrev_b32_e32 v2, 1, v146
	v_ashrrev_i32_e32 v3, 31, v2
	s_add_u32 s4, s84, s3
	s_addc_u32 s5, s85, 0
	v_lshlrev_b64 v[10:11], 1, v[2:3]
	v_lshl_add_u64 v[16:17], s[4:5], 0, v[10:11]
	s_or_b32 s4, s2, s6
	s_mul_i32 s3, s4, 0x1800
	s_add_u32 s8, s84, s3
	s_addc_u32 s9, s85, 0
	v_lshl_add_u64 v[4:5], s[8:9], 0, v[10:11]
	s_movk_i32 s3, 0x2000
	v_add_co_u32_e32 v18, vcc, s3, v4
	s_movk_i32 s5, 0x3000
	s_nop 0
	v_addc_co_u32_e32 v19, vcc, 0, v5, vcc
	v_add_co_u32_e32 v6, vcc, s5, v4
	s_movk_i32 s3, 0x5000
	s_nop 0
	v_addc_co_u32_e32 v7, vcc, 0, v5, vcc
	v_add_co_u32_e32 v14, vcc, s3, v4
	v_lshl_add_u64 v[20:21], s[84:85], 0, v[10:11]
	s_mul_i32 s26, s4, 0xc00
	v_addc_co_u32_e32 v15, vcc, 0, v5, vcc
	v_lshl_add_u64 v[22:23], s[26:27], 1, v[20:21]
	global_load_dword v38, v[6:7], off offset:2048 nt
	global_load_dword v36, v[14:15], off nt
	global_load_dword v43, v[22:23], off nt
	v_add_co_u32_e32 v6, vcc, s80, v4
	s_mov_b32 s3, 0x9000
	s_nop 0
	v_addc_co_u32_e32 v7, vcc, 0, v5, vcc
	v_add_co_u32_e32 v12, vcc, s82, v4
	global_load_dword v41, v[18:19], off nt
	global_load_dword v34, v[6:7], off offset:2048 nt
	v_addc_co_u32_e32 v13, vcc, 0, v5, vcc
	global_load_dword v29, v[12:13], off nt
	v_add_co_u32_e32 v6, vcc, s3, v4
	s_mov_b32 s3, 0xb000
	s_nop 0
	v_addc_co_u32_e32 v7, vcc, 0, v5, vcc
	global_load_dword v40, v[16:17], off offset:2048 nt
	global_load_dword v28, v[6:7], off offset:2048 nt
	v_add_co_u32_e32 v6, vcc, s3, v4
	s_min_u32 s3, s6, 0xf7
	s_or_b32 s3, s3, s2
	v_addc_co_u32_e32 v7, vcc, 0, v5, vcc
	s_mulk_i32 s3, 0x1800
	s_add_i32 s3, s3, 0xc000
	v_add_co_u32_e32 v24, vcc, s75, v22
	s_add_u32 s8, s84, s3
	s_nop 0
	v_addc_co_u32_e32 v25, vcc, 0, v23, vcc
	s_addc_u32 s9, s85, 0
	v_add_co_u32_e32 v22, vcc, s5, v22
	v_lshl_add_u64 v[8:9], s[8:9], 0, v[10:11]
	s_nop 0
	v_addc_co_u32_e32 v23, vcc, 0, v23, vcc
	s_add_i32 s8, s26, 0x2400
	s_mov_b32 s9, s27
	s_add_i32 s18, s6, -15
	global_load_dword v37, v[22:23], off nt
	v_lshl_add_u64 v[22:23], s[8:9], 1, v[20:21]
	s_add_i32 s8, s26, 0x3000
	s_max_i32 s3, s18, 0
	global_load_dword v35, v[22:23], off nt
	v_lshl_add_u64 v[22:23], s[8:9], 1, v[20:21]
	s_add_i32 s8, s26, 0x3c00
	s_add_i32 s3, s2, s3
	global_load_dword v33, v[22:23], off nt
	v_lshl_add_u64 v[22:23], s[8:9], 1, v[20:21]
	s_add_i32 s8, s26, 0x4800
	s_addk_i32 s26, 0x5400
	s_mulk_i32 s3, 0x1800
	global_load_dword v32, v[22:23], off nt
	v_lshl_add_u64 v[22:23], s[8:9], 1, v[20:21]
	s_add_u32 s8, s84, s3
	s_addc_u32 s9, s85, 0
	s_add_i32 s19, s6, -14
	s_max_i32 s3, s19, 0
	s_add_i32 s3, s2, s3
	v_lshl_add_u64 v[20:21], s[26:27], 1, v[20:21]
	s_mulk_i32 s3, 0x1800
	global_load_dword v31, v[22:23], off nt
	global_load_dword v30, v[20:21], off nt
	v_lshl_add_u64 v[20:21], s[8:9], 0, v[10:11]
	s_add_u32 s8, s84, s3
	s_addc_u32 s9, s85, 0
	s_add_i32 s20, s6, -13
	s_max_i32 s3, s20, 0
	s_add_i32 s3, s2, s3
	s_mulk_i32 s3, 0x1800
	v_lshl_add_u64 v[22:23], s[8:9], 0, v[10:11]
	s_add_u32 s8, s84, s3
	v_add_co_u32_e32 v20, vcc, s75, v20
	s_addc_u32 s9, s85, 0
	s_add_i32 s21, s6, -12
	v_addc_co_u32_e32 v21, vcc, 0, v21, vcc
	s_max_i32 s3, s21, 0
	v_add_co_u32_e32 v22, vcc, s75, v22
	s_add_i32 s3, s2, s3
	s_nop 0
	v_addc_co_u32_e32 v23, vcc, 0, v23, vcc
	s_mulk_i32 s3, 0x1800
	global_load_dword v39, v[24:25], off offset:2048 nt
	global_load_dword v42, v[4:5], off offset:2048 nt
	global_load_dword v27, v[6:7], off nt
	global_load_dword v26, v[8:9], off offset:2048 nt
	v_readlane_b32 s36, v253, 32
	global_load_dword v20, v[20:21], off nt
	v_readlane_b32 s46, v253, 42
	global_load_dword v21, v[22:23], off nt
	v_lshl_add_u64 v[22:23], s[8:9], 0, v[10:11]
	s_add_u32 s8, s84, s3
	s_addc_u32 s9, s85, 0
	s_add_i32 s22, s6, -11
	s_max_i32 s3, s22, 0
	s_add_i32 s3, s2, s3
	s_mulk_i32 s3, 0x1800
	v_lshl_add_u64 v[24:25], s[8:9], 0, v[10:11]
	s_add_u32 s8, s84, s3
	v_add_co_u32_e32 v22, vcc, s75, v22
	s_addc_u32 s9, s85, 0
	s_add_i32 s23, s6, -10
	v_addc_co_u32_e32 v23, vcc, 0, v23, vcc
	s_max_i32 s3, s23, 0
	v_add_co_u32_e32 v24, vcc, s75, v24
	s_add_i32 s3, s2, s3
	s_nop 0
	v_addc_co_u32_e32 v25, vcc, 0, v25, vcc
	s_mulk_i32 s3, 0x1800
	global_load_dword v22, v[22:23], off nt
	v_readlane_b32 s47, v253, 43
	global_load_dword v23, v[24:25], off nt
	v_lshl_add_u64 v[24:25], s[8:9], 0, v[10:11]
	s_add_u32 s8, s84, s3
	s_addc_u32 s9, s85, 0
	s_add_i32 s24, s6, -9
	s_max_i32 s3, s24, 0
	s_add_i32 s3, s2, s3
	s_mulk_i32 s3, 0x1800
	v_lshl_add_u64 v[44:45], s[8:9], 0, v[10:11]
	s_add_u32 s8, s84, s3
	v_add_co_u32_e32 v24, vcc, s75, v24
	s_addc_u32 s9, s85, 0
	s_add_i32 s25, s6, -8
	v_addc_co_u32_e32 v25, vcc, 0, v25, vcc
	s_max_i32 s3, s25, 0
	v_add_co_u32_e32 v44, vcc, s75, v44
	s_add_i32 s3, s2, s3
	s_nop 0
	v_addc_co_u32_e32 v45, vcc, 0, v45, vcc
	s_mulk_i32 s3, 0x1800
	global_load_dword v24, v[24:25], off nt
	v_readlane_b32 s37, v253, 33
	global_load_dword v25, v[44:45], off nt
	v_lshl_add_u64 v[44:45], s[8:9], 0, v[10:11]
	s_add_u32 s8, s84, s3
	s_addc_u32 s9, s85, 0
	s_add_i32 s28, s6, -7
	s_max_i32 s3, s28, 0
	v_add_co_u32_e32 v44, vcc, s75, v44
	s_add_i32 s3, s2, s3
	s_nop 0
	v_addc_co_u32_e32 v45, vcc, 0, v45, vcc
	s_mulk_i32 s3, 0x1800
	global_load_dword v82, v[44:45], off nt
	v_lshl_add_u64 v[44:45], s[8:9], 0, v[10:11]
	s_add_u32 s8, s84, s3
	s_addc_u32 s9, s85, 0
	s_add_i32 s29, s6, -6
	s_max_i32 s3, s29, 0
; template <int NT>
; __device__ __forceinline__ void even_conv_unit(const Params& p, LAS unsigned char* lds, int base, int T, int t0, int tid_in, int lane, int wave) {
;     ...
;     for (int i = 0; i < NT + 2; ++i) { const int tc = min(max(t0 - 1 + i, 0), T - 1); pv[i] = *(const unsigned*)(Z3 + (size_t)(base + tc) * ZE_LD + 1024 + 2 * tid); }
; #pragma unroll
;     for (int i = 0; i < NT; ++i) bgv[i] = *(const unsigned*)(Z3 + (size_t)(base + t0 + i) * ZE_LD + 2 * tid);
; #pragma unroll
;     for (int j = 0; j < NR; ++j) { const int tc = min(max(t0 - 15 + j, 0), T - 1); xr[j] = *(const unsigned*)(Z3 + (size_t)(base + tc) * ZE_LD + 2048 + 2 * tid); }
;     const f32x2 cbias = *(const f32x2*)(ccb + 2 * tid);
;     if (t0 == 0) pv[0] = 0u;
;     if (t0 + NT == T) pv[NT + 1] = 0u;
;     { const f32x2 w0 = *(const f32x2*)(scw + 2 * tid), w1 = *(const f32x2*)(scw + 1024 + 2 * tid), w2 = *(const f32x2*)(scw + 2048 + 2 * tid), b = *(const f32x2*)(scb + 2 * tid);
	v_add_co_u32_e32 v44, vcc, s75, v44
	s_add_i32 s3, s2, s3
	s_nop 0
	v_addc_co_u32_e32 v45, vcc, 0, v45, vcc
	s_mulk_i32 s3, 0x1800
	global_load_dword v83, v[44:45], off nt
	v_lshl_add_u64 v[44:45], s[8:9], 0, v[10:11]
	s_add_u32 s8, s84, s3
	s_addc_u32 s9, s85, 0
	s_add_i32 s30, s6, -5
	s_max_i32 s3, s30, 0
	v_add_co_u32_e32 v44, vcc, s75, v44
	s_add_i32 s3, s2, s3
	s_nop 0
	v_addc_co_u32_e32 v45, vcc, 0, v45, vcc
	s_mulk_i32 s3, 0x1800
	global_load_dword v87, v[44:45], off nt
	v_lshl_add_u64 v[44:45], s[8:9], 0, v[10:11]
	s_add_u32 s8, s84, s3
	s_addc_u32 s9, s85, 0
	s_add_i32 s31, s6, -4
	s_max_i32 s3, s31, 0
	v_add_co_u32_e32 v44, vcc, s75, v44
	s_add_i32 s3, s2, s3
	s_nop 0
	v_addc_co_u32_e32 v45, vcc, 0, v45, vcc
	s_mulk_i32 s3, 0x1800
	global_load_dword v89, v[44:45], off nt
	v_lshl_add_u64 v[44:45], s[8:9], 0, v[10:11]
	s_add_u32 s8, s84, s3
	s_addc_u32 s9, s85, 0
	s_add_i32 s34, s6, -3
	s_max_i32 s3, s34, 0
	v_add_co_u32_e32 v44, vcc, s75, v44
	s_add_i32 s3, s2, s3
	s_nop 0
	v_addc_co_u32_e32 v45, vcc, 0, v45, vcc
	s_mulk_i32 s3, 0x1800
	global_load_dword v91, v[44:45], off nt
	v_lshl_add_u64 v[44:45], s[8:9], 0, v[10:11]
	s_add_u32 s8, s84, s3
	s_addc_u32 s9, s85, 0
	s_add_i32 s35, s6, -2
	v_add_co_u32_e32 v44, vcc, s75, v44
	s_max_i32 s3, s35, 0
	s_nop 0
	v_addc_co_u32_e32 v45, vcc, 0, v45, vcc
	s_add_i32 s3, s2, s3
	global_load_dword v93, v[44:45], off nt
	v_lshl_add_u64 v[44:45], s[8:9], 0, v[10:11]
	s_mulk_i32 s3, 0x1800
	v_add_co_u32_e32 v44, vcc, s75, v44
	s_add_u32 s8, s84, s3
	s_nop 0
	v_addc_co_u32_e32 v45, vcc, 0, v45, vcc
	s_addc_u32 s9, s85, 0
	global_load_dword v95, v[44:45], off nt
	v_lshl_add_u64 v[44:45], s[8:9], 0, v[10:11]
	v_add_co_u32_e32 v44, vcc, s75, v44
	s_movk_i32 s3, 0x7000
	s_nop 0
	v_addc_co_u32_e32 v45, vcc, 0, v45, vcc
	v_add_co_u32_e32 v16, vcc, s75, v16
	global_load_dword v97, v[44:45], off nt
	s_nop 0
	v_addc_co_u32_e32 v17, vcc, 0, v17, vcc
	global_load_dword v99, v[16:17], off nt
	v_add_co_u32_e32 v16, vcc, s75, v4
	v_readlane_b32 s38, v253, 34
	s_nop 0
	v_addc_co_u32_e32 v17, vcc, 0, v5, vcc
	global_load_dword v101, v[16:17], off nt
	global_load_dword v103, v[18:19], off offset:2048 nt
	v_add_co_u32_e32 v16, vcc, s86, v4
	v_readlane_b32 s39, v253, 35
	s_nop 0
	v_addc_co_u32_e32 v17, vcc, 0, v5, vcc
	global_load_dword v105, v[16:17], off nt
	global_load_dword v107, v[14:15], off offset:2048 nt
	v_add_co_u32_e32 v14, vcc, s3, v4
	s_min_u32 s3, s6, 0xf6
	s_or_b32 s3, s3, s2
	s_mulk_i32 s3, 0x1800
	s_add_i32 s3, s3, 0xd800
	v_addc_co_u32_e32 v15, vcc, 0, v5, vcc
	s_add_u32 s8, s84, s3
	v_add_co_u32_e32 v4, vcc, s81, v4
	s_addc_u32 s9, s85, 0
	s_min_u32 s3, s6, 0xf5
	v_addc_co_u32_e32 v5, vcc, 0, v5, vcc
	s_or_b32 s3, s3, s2
	global_load_dword v109, v[14:15], off nt
	global_load_dword v111, v[12:13], off offset:2048 nt
	global_load_dword v113, v[4:5], off nt
	global_load_dword v115, v[6:7], off offset:2048 nt
	v_add_co_u32_e32 v4, vcc, s75, v8
	s_mulk_i32 s3, 0x1800
	s_nop 0
	v_addc_co_u32_e32 v5, vcc, 0, v9, vcc
	s_add_i32 s3, s3, 0xf000
	global_load_dword v117, v[4:5], off nt
	v_lshl_add_u64 v[4:5], s[8:9], 0, v[10:11]
	s_add_u32 s8, s84, s3
	s_addc_u32 s9, s85, 0
	s_min_u32 s3, s6, 0xf4
	s_or_b32 s3, s3, s2
	v_add_co_u32_e32 v4, vcc, s75, v4
	s_mulk_i32 s3, 0x1800
	s_nop 0
	v_addc_co_u32_e32 v5, vcc, 0, v5, vcc
	s_add_i32 s3, s3, 0x10800
	global_load_dword v119, v[4:5], off nt
	v_lshl_add_u64 v[4:5], s[8:9], 0, v[10:11]
	s_add_u32 s8, s84, s3
	s_addc_u32 s9, s85, 0
	s_min_u32 s3, s6, 0xf3
	s_or_b32 s3, s3, s2
	v_add_co_u32_e32 v4, vcc, s75, v4
	s_mulk_i32 s3, 0x1800
	s_nop 0
	v_addc_co_u32_e32 v5, vcc, 0, v5, vcc
	s_add_i32 s3, s3, 0x12000
	global_load_dword v121, v[4:5], off nt
	v_lshl_add_u64 v[4:5], s[8:9], 0, v[10:11]
	s_add_u32 s8, s84, s3
	s_addc_u32 s9, s85, 0
	s_min_u32 s3, s6, 0xf2
	s_or_b32 s3, s3, s2
; template <int NT>
; __device__ __forceinline__ void even_conv_unit(const Params& p, LAS unsigned char* lds, int base, int T, int t0, int tid_in, int lane, int wave) {
;     ...
;     for (int i = 0; i < NT + 2; ++i) { const int tc = min(max(t0 - 1 + i, 0), T - 1); pv[i] = *(const unsigned*)(Z3 + (size_t)(base + tc) * ZE_LD + 1024 + 2 * tid); }
; #pragma unroll
;     for (int i = 0; i < NT; ++i) bgv[i] = *(const unsigned*)(Z3 + (size_t)(base + t0 + i) * ZE_LD + 2 * tid);
; #pragma unroll
;     for (int j = 0; j < NR; ++j) { const int tc = min(max(t0 - 15 + j, 0), T - 1); xr[j] = *(const unsigned*)(Z3 + (size_t)(base + tc) * ZE_LD + 2048 + 2 * tid); }
;     const f32x2 cbias = *(const f32x2*)(ccb + 2 * tid);
;     if (t0 == 0) pv[0] = 0u;
;     if (t0 + NT == T) pv[NT + 1] = 0u;
;     { const f32x2 w0 = *(const f32x2*)(scw + 2 * tid), w1 = *(const f32x2*)(scw + 1024 + 2 * tid), w2 = *(const f32x2*)(scw + 2048 + 2 * tid), b = *(const f32x2*)(scb + 2 * tid);
	v_add_co_u32_e32 v4, vcc, s75, v4
	s_mulk_i32 s3, 0x1800
	s_nop 0
	v_addc_co_u32_e32 v5, vcc, 0, v5, vcc
	s_add_i32 s3, s3, 0x13800
	global_load_dword v123, v[4:5], off nt
	v_lshl_add_u64 v[4:5], s[8:9], 0, v[10:11]
	s_add_u32 s8, s84, s3
	s_addc_u32 s9, s85, 0
	s_min_u32 s3, s6, 0xf1
	s_or_b32 s3, s3, s2
	v_add_co_u32_e32 v4, vcc, s75, v4
	s_mulk_i32 s3, 0x1800
	s_nop 0
	v_addc_co_u32_e32 v5, vcc, 0, v5, vcc
	s_add_i32 s3, s3, 0x15000
	global_load_dword v125, v[4:5], off nt
	v_lshl_add_u64 v[4:5], s[8:9], 0, v[10:11]
	s_add_u32 s8, s84, s3
	s_addc_u32 s9, s85, 0
	s_min_u32 s3, s6, 0xf0
	s_or_b32 s3, s3, s2
	v_add_co_u32_e32 v4, vcc, s75, v4
	s_mulk_i32 s3, 0x1800
	s_nop 0
	v_addc_co_u32_e32 v5, vcc, 0, v5, vcc
	s_add_i32 s3, s3, 0x16800
	global_load_dword v127, v[4:5], off nt
	v_lshl_add_u64 v[4:5], s[8:9], 0, v[10:11]
	s_add_u32 s8, s84, s3
	s_addc_u32 s9, s85, 0
	s_min_u32 s3, s6, 0xef
	s_or_b32 s3, s3, s2
	v_add_co_u32_e32 v4, vcc, s75, v4
	s_mulk_i32 s3, 0x1800
	s_nop 0
	v_addc_co_u32_e32 v5, vcc, 0, v5, vcc
	s_add_i32 s3, s3, 0x18000
	global_load_dword v129, v[4:5], off nt
	v_lshl_add_u64 v[4:5], s[8:9], 0, v[10:11]
	s_add_u32 s8, s84, s3
	s_addc_u32 s9, s85, 0
	s_min_u32 s3, s6, 0xee
	s_or_b32 s3, s3, s2
	v_add_co_u32_e32 v4, vcc, s75, v4
	s_mulk_i32 s3, 0x1800
	s_nop 0
	v_addc_co_u32_e32 v5, vcc, 0, v5, vcc
	s_add_i32 s3, s3, 0x19800
	global_load_dword v131, v[4:5], off nt
	v_lshl_add_u64 v[4:5], s[8:9], 0, v[10:11]
	s_add_u32 s8, s84, s3
	s_addc_u32 s9, s85, 0
	s_min_u32 s3, s6, 0xed
	s_or_b32 s3, s3, s2
	v_add_co_u32_e32 v4, vcc, s75, v4
	s_mulk_i32 s3, 0x1800
	s_nop 0
	v_addc_co_u32_e32 v5, vcc, 0, v5, vcc
	s_add_i32 s3, s3, 0x1b000
	global_load_dword v133, v[4:5], off nt
	v_lshl_add_u64 v[4:5], s[8:9], 0, v[10:11]
	s_add_u32 s8, s84, s3
	s_addc_u32 s9, s85, 0
	s_min_u32 s3, s6, 0xec
	s_or_b32 s3, s3, s2
	v_add_co_u32_e32 v4, vcc, s75, v4
	s_mulk_i32 s3, 0x1800
	s_nop 0
	v_addc_co_u32_e32 v5, vcc, 0, v5, vcc
	s_add_i32 s3, s3, 0x1c800
	global_load_dword v139, v[4:5], off nt
	v_lshl_add_u64 v[4:5], s[8:9], 0, v[10:11]
	s_add_u32 s8, s84, s3
	s_addc_u32 s9, s85, 0
	s_min_u32 s3, s6, 0xeb
	s_or_b32 s3, s3, s2
	v_add_co_u32_e32 v4, vcc, s75, v4
	s_mulk_i32 s3, 0x1800
	s_nop 0
	v_addc_co_u32_e32 v5, vcc, 0, v5, vcc
	s_add_i32 s3, s3, 0x1e000
	global_load_dword v137, v[4:5], off nt
	v_lshl_add_u64 v[4:5], s[8:9], 0, v[10:11]
	s_add_u32 s8, s84, s3
	s_addc_u32 s9, s85, 0
	s_min_u32 s3, s6, 0xea
	s_or_b32 s3, s3, s2
	v_add_co_u32_e32 v4, vcc, s75, v4
	s_mulk_i32 s3, 0x1800
	s_nop 0
	v_addc_co_u32_e32 v5, vcc, 0, v5, vcc
	s_add_i32 s3, s3, 0x1f800
	global_load_dword v135, v[4:5], off nt
	v_lshl_add_u64 v[4:5], s[8:9], 0, v[10:11]
	s_add_u32 s8, s84, s3
	s_addc_u32 s9, s85, 0
	s_min_u32 s3, s6, 0xe9
	v_add_co_u32_e32 v4, vcc, s75, v4
	s_or_b32 s2, s3, s2
	s_nop 0
	v_addc_co_u32_e32 v5, vcc, 0, v5, vcc
	s_mulk_i32 s2, 0x1800
	global_load_dword v134, v[4:5], off nt
	v_lshl_add_u64 v[4:5], s[8:9], 0, v[10:11]
	s_add_i32 s2, s2, 0x21000
	v_add_co_u32_e32 v4, vcc, s75, v4
	s_add_u32 s2, s84, s2
	s_nop 0
	v_addc_co_u32_e32 v5, vcc, 0, v5, vcc
	s_addc_u32 s3, s85, 0
	global_load_dword v136, v[4:5], off nt
	v_lshl_add_u64 v[4:5], s[2:3], 0, v[10:11]
	v_add_co_u32_e32 v4, vcc, 0x1000, v4
	s_mov_b64 s[2:3], -1
	s_nop 0
	v_addc_co_u32_e32 v5, vcc, 0, v5, vcc
	global_load_dword v147, v[4:5], off nt
	v_lshl_add_u64 v[4:5], v[2:3], 2, s[46:47]
	global_load_dwordx2 v[4:5], v[4:5], off
	s_cmpk_gt_i32 s6, 0xf7
	v_readlane_b32 s40, v253, 36
	v_readlane_b32 s41, v253, 37
	v_readlane_b32 s42, v253, 38
	v_readlane_b32 s43, v253, 39
	v_readlane_b32 s44, v253, 40
	v_readlane_b32 s45, v253, 41
	v_readlane_b32 s48, v253, 44
	v_readlane_b32 s49, v253, 45
	v_readlane_b32 s50, v253, 46
	v_readlane_b32 s51, v253, 47
	s_cbranch_scc0 .LBB0_686
	s_mov_b64 s[2:3], 0

; template <int NT>
; __device__ __forceinline__ void even_conv_unit(const Params& p, LAS unsigned char* lds, int base, int T, int t0, int tid_in, int lane, int wave) {
;     ...
;     unsigned pv[NT + 2], bgv[NT], xr[NR];
; #pragma unroll
;     for (int i = 0; i < NT + 2; ++i) { const int tc = min(max(t0 - 1 + i, 0), T - 1); pv[i] = *(const unsigned*)(Z3 + (size_t)(base + tc) * ZE_LD + 1024 + 2 * tid); }
; #pragma unroll
;     for (int i = 0; i < NT; ++i) bgv[i] = *(const unsigned*)(Z3 + (size_t)(base + t0 + i) * ZE_LD + 2 * tid);
; #pragma unroll
;     for (int j = 0; j < NR; ++j) { const int tc = min(max(t0 - 15 + j, 0), T - 1); xr[j] = *(const unsigned*)(Z3 + (size_t)(base + tc) * ZE_LD + 2048 + 2 * tid); }
; __device__ __forceinline__ void even_conv_phase(const Params& p, LAS unsigned char* lds, int tid, int lane, int wave) {
;     for (int k = blockIdx.x; k < 512 + 256; k += gridDim.x) {
;         if (k < 512) { const int u = (k & 7) * 64 + (k >> 3); even_conv_unit<32>(p, lds, (u >> 6) * SEQ, SEQ, (u & 63) * 32, tid, lane, wave); }
.LBB0_729:
	s_and_b64 vcc, exec, s[2:3]
	s_cbranch_vccz .LBB0_682
	s_and_b32 s2, s33, 0x1c0
	s_ashr_i32 s4, s72, 3
	s_add_i32 s2, s2, s4
	s_lshl_b32 s2, s2, 5
	s_and_b32 s3, s2, 0xfffff800
	s_lshl_b32 s2, s4, 5
	s_and_b32 s26, s2, 0x7e0
	v_writelane_b32 v252, s68, 10
	s_add_i32 s2, s26, -1
	v_writelane_b32 v252, s2, 11
	s_max_i32 s2, s2, 0
	v_mov_b32_e32 v196, v0
	s_or_b32 s2, s2, s3
	s_mul_hi_i32 s5, s2, 0x1800
	s_waitcnt vmcnt(0)
	v_lshlrev_b32_e32 v2, 1, v196
	s_mulk_i32 s2, 0x1800
	v_ashrrev_i32_e32 v3, 31, v2
	s_add_u32 s4, s84, s2
	s_addc_u32 s5, s85, s5
	v_lshlrev_b64 v[34:35], 1, v[2:3]
	s_or_b32 s78, s3, s26
	v_lshl_add_u64 v[4:5], s[4:5], 0, v[34:35]
	s_mul_i32 s4, s78, 0x1800
	s_mul_hi_i32 s2, s78, 0x1800
	s_add_u32 s4, s84, s4
	s_addc_u32 s5, s85, s2
	s_or_b32 s76, s78, 1
	v_lshl_add_u64 v[6:7], s[4:5], 0, v[34:35]
	s_mul_i32 s4, s76, 0x1800
	s_mul_hi_i32 s2, s76, 0x1800
	s_add_u32 s4, s84, s4
	s_addc_u32 s5, s85, s2
	s_or_b32 s34, s78, 2
	v_lshl_add_u64 v[8:9], s[4:5], 0, v[34:35]
	s_mul_i32 s4, s34, 0x1800
	s_mul_hi_i32 s2, s34, 0x1800
	s_add_u32 s4, s84, s4
	s_addc_u32 s5, s85, s2
	s_or_b32 s22, s78, 3
	v_lshl_add_u64 v[10:11], s[4:5], 0, v[34:35]
	s_mul_i32 s4, s22, 0x1800
	s_mul_hi_i32 s2, s22, 0x1800
	s_add_u32 s4, s84, s4
	s_addc_u32 s5, s85, s2
	s_or_b32 s38, s78, 4
	v_lshl_add_u64 v[12:13], s[4:5], 0, v[34:35]
	s_mul_i32 s4, s38, 0x1800
	s_mul_hi_i32 s2, s38, 0x1800
	s_add_u32 s4, s84, s4
	s_addc_u32 s5, s85, s2
	s_or_b32 s36, s78, 5
	v_lshl_add_u64 v[14:15], s[4:5], 0, v[34:35]
	s_mul_i32 s4, s36, 0x1800
	s_mul_hi_i32 s2, s36, 0x1800
	s_add_u32 s4, s84, s4
	s_addc_u32 s5, s85, s2
	s_or_b32 s2, s78, 6
	v_lshl_add_u64 v[16:17], s[4:5], 0, v[34:35]
	s_mul_i32 s4, s2, 0x1800
	s_mul_hi_i32 s5, s2, 0x1800
	s_add_u32 s4, s84, s4
	s_addc_u32 s5, s85, s5
	s_or_b32 s46, s78, 7
	v_lshl_add_u64 v[18:19], s[4:5], 0, v[34:35]
	s_mul_i32 s4, s46, 0x1800
	s_mul_hi_i32 s5, s46, 0x1800
	s_add_u32 s4, s84, s4
	s_addc_u32 s5, s85, s5
	s_or_b32 s20, s78, 8
	v_lshl_add_u64 v[20:21], s[4:5], 0, v[34:35]
	s_mul_i32 s4, s20, 0x1800
	s_mul_hi_i32 s5, s20, 0x1800
	s_add_u32 s4, s84, s4
	s_addc_u32 s5, s85, s5
	s_or_b32 s96, s78, 9
	v_lshl_add_u64 v[22:23], s[4:5], 0, v[34:35]
	s_mul_i32 s4, s96, 0x1800
	s_mul_hi_i32 s5, s96, 0x1800
	s_add_u32 s4, s84, s4
	s_addc_u32 s5, s85, s5
	s_or_b32 s94, s78, 10
	v_lshl_add_u64 v[24:25], s[4:5], 0, v[34:35]
	s_mul_i32 s4, s94, 0x1800
	s_mul_hi_i32 s5, s94, 0x1800
	s_add_u32 s4, s84, s4
	s_addc_u32 s5, s85, s5
	s_or_b32 s92, s78, 11
	v_lshl_add_u64 v[26:27], s[4:5], 0, v[34:35]
	s_mul_i32 s4, s92, 0x1800
	s_mul_hi_i32 s5, s92, 0x1800
	s_add_u32 s4, s84, s4
	s_addc_u32 s5, s85, s5
	s_or_b32 s90, s78, 12
	v_lshl_add_u64 v[28:29], s[4:5], 0, v[34:35]
	s_mul_i32 s4, s90, 0x1800
	s_mul_hi_i32 s5, s90, 0x1800
	s_add_u32 s4, s84, s4
	s_addc_u32 s5, s85, s5
	s_or_b32 s88, s78, 13
	v_lshl_add_u64 v[30:31], s[4:5], 0, v[34:35]
	s_mul_i32 s4, s88, 0x1800
	s_mul_hi_i32 s5, s88, 0x1800
	s_add_u32 s4, s84, s4
	s_addc_u32 s5, s85, s5
	s_or_b32 s42, s78, 14
	v_lshl_add_u64 v[32:33], s[4:5], 0, v[34:35]
	s_mul_i32 s4, s42, 0x1800
	s_mul_hi_i32 s5, s42, 0x1800
	s_add_u32 s4, s84, s4
	s_addc_u32 s5, s85, s5
	s_or_b32 s44, s78, 15
	v_lshl_add_u64 v[36:37], s[4:5], 0, v[34:35]
	s_mul_i32 s4, s44, 0x1800
	s_mul_hi_i32 s5, s44, 0x1800
	s_add_u32 s4, s84, s4
	s_addc_u32 s5, s85, s5
	s_or_b32 s30, s78, 16
	v_lshl_add_u64 v[38:39], s[4:5], 0, v[34:35]
	s_mul_i32 s4, s30, 0x1800
	s_mul_hi_i32 s5, s30, 0x1800
	s_add_u32 s4, s84, s4
	s_addc_u32 s5, s85, s5
	s_or_b32 s28, s78, 17
	v_lshl_add_u64 v[40:41], s[4:5], 0, v[34:35]
	s_mul_i32 s4, s28, 0x1800
	s_mul_hi_i32 s5, s28, 0x1800
	s_add_u32 s4, s84, s4
	s_addc_u32 s5, s85, s5
	s_or_b32 s50, s78, 18
	v_lshl_add_u64 v[42:43], s[4:5], 0, v[34:35]
	s_mul_i32 s4, s50, 0x1800
	s_mul_hi_i32 s5, s50, 0x1800
	s_add_u32 s4, s84, s4
	s_addc_u32 s5, s85, s5
	s_or_b32 s48, s78, 19
	v_lshl_add_u64 v[44:45], s[4:5], 0, v[34:35]
	s_mul_i32 s4, s48, 0x1800
	s_mul_hi_i32 s5, s48, 0x1800
	s_add_u32 s4, s84, s4
	s_addc_u32 s5, s85, s5
	s_or_b32 s24, s78, 20
	v_lshl_add_u64 v[46:47], s[4:5], 0, v[34:35]
	s_mul_i32 s4, s24, 0x1800
	s_mul_hi_i32 s5, s24, 0x1800
	s_add_u32 s4, s84, s4
	s_addc_u32 s5, s85, s5
	s_or_b32 s80, s78, 21
	v_lshl_add_u64 v[48:49], s[4:5], 0, v[34:35]
	s_mul_i32 s4, s80, 0x1800
	s_mul_hi_i32 s5, s80, 0x1800
	s_add_u32 s4, s84, s4
	s_addc_u32 s5, s85, s5
	s_or_b32 s40, s78, 22
	s_mul_i32 s6, s40, 0x1800
	v_lshl_add_u64 v[50:51], s[4:5], 0, v[34:35]
	s_mul_hi_i32 s5, s40, 0x1800
	s_add_u32 s6, s84, s6
	s_addc_u32 s7, s85, s5
	s_or_b32 s82, s78, 23
	v_lshl_add_u64 v[52:53], s[6:7], 0, v[34:35]
	s_mul_i32 s6, s82, 0x1800
	s_mul_hi_i32 s5, s82, 0x1800
	s_add_u32 s6, s84, s6
	s_addc_u32 s7, s85, s5
	s_or_b32 s18, s78, 24
	v_lshl_add_u64 v[54:55], s[6:7], 0, v[34:35]
	s_mul_i32 s6, s18, 0x1800
	s_mul_hi_i32 s5, s18, 0x1800
	s_add_u32 s6, s84, s6
	s_addc_u32 s7, s85, s5
	s_or_b32 s16, s78, 25
	v_lshl_add_u64 v[56:57], s[6:7], 0, v[34:35]
	s_mul_i32 s6, s16, 0x1800
	s_mul_hi_i32 s5, s16, 0x1800
	s_add_u32 s6, s84, s6
	s_addc_u32 s7, s85, s5
	s_or_b32 s14, s78, 26
	v_lshl_add_u64 v[58:59], s[6:7], 0, v[34:35]
	s_mul_i32 s6, s14, 0x1800
	s_mul_hi_i32 s5, s14, 0x1800
	s_add_u32 s6, s84, s6
	s_addc_u32 s7, s85, s5
	s_or_b32 s12, s78, 27
	v_lshl_add_u64 v[60:61], s[6:7], 0, v[34:35]
	s_mul_i32 s6, s12, 0x1800
	v_lshl_add_u64 v[82:83], s[84:85], 0, v[34:35]
	s_mul_hi_i32 s5, s12, 0x1800
	s_add_u32 s6, s84, s6
	v_mad_i64_i32 v[84:85], s[70:71], s78, v195, v[82:83]
	global_load_dword v141, v[20:21], off offset:2048 nt
	global_load_dword v203, v[84:85], off nt
	s_addc_u32 s7, s85, s5
	s_or_b32 s10, s78, 28
; template <int NT>
; __device__ __forceinline__ void even_conv_unit(const Params& p, LAS unsigned char* lds, int base, int T, int t0, int tid_in, int lane, int wave) {
;     ...
;     for (int i = 0; i < NT + 2; ++i) { const int tc = min(max(t0 - 1 + i, 0), T - 1); pv[i] = *(const unsigned*)(Z3 + (size_t)(base + tc) * ZE_LD + 1024 + 2 * tid); }
; #pragma unroll
;     for (int i = 0; i < NT; ++i) bgv[i] = *(const unsigned*)(Z3 + (size_t)(base + t0 + i) * ZE_LD + 2 * tid);
; #pragma unroll
;     for (int j = 0; j < NR; ++j) { const int tc = min(max(t0 - 15 + j, 0), T - 1); xr[j] = *(const unsigned*)(Z3 + (size_t)(base + tc) * ZE_LD + 2048 + 2 * tid); }
	v_mad_i64_i32 v[84:85], s[70:71], s76, v195, v[82:83]
	global_load_dword v140, v[22:23], off offset:2048 nt
	global_load_dword v202, v[84:85], off nt
	v_lshl_add_u64 v[62:63], s[6:7], 0, v[34:35]
	s_mul_i32 s6, s10, 0x1800
	v_mad_i64_i32 v[84:85], s[70:71], s34, v195, v[82:83]
	global_load_dword v138, v[24:25], off offset:2048 nt
	global_load_dword v201, v[84:85], off nt
	s_mul_hi_i32 s5, s10, 0x1800
	s_add_u32 s6, s84, s6
	v_mad_i64_i32 v[84:85], s[70:71], s22, v195, v[82:83]
	global_load_dword v135, v[26:27], off offset:2048 nt
	global_load_dword v200, v[84:85], off nt
	s_addc_u32 s7, s85, s5
	s_or_b32 s4, s78, 29
	v_mad_i64_i32 v[84:85], s[70:71], s38, v195, v[82:83]
	global_load_dword v133, v[28:29], off offset:2048 nt
	global_load_dword v186, v[84:85], off nt
	v_lshl_add_u64 v[64:65], s[6:7], 0, v[34:35]
	s_mul_i32 s6, s4, 0x1800
	v_mad_i64_i32 v[84:85], s[70:71], s36, v195, v[82:83]
	global_load_dword v132, v[30:31], off offset:2048 nt
	global_load_dword v182, v[84:85], off nt
	s_mul_hi_i32 s5, s4, 0x1800
	s_add_u32 s6, s84, s6
	v_mad_i64_i32 v[84:85], s[70:71], s2, v195, v[82:83]
	global_load_dword v130, v[32:33], off offset:2048 nt
	global_load_dword v180, v[84:85], off nt
	s_addc_u32 s7, s85, s5
	s_or_b32 s8, s78, 30
	v_mad_i64_i32 v[84:85], s[70:71], s46, v195, v[82:83]
	global_load_dword v125, v[36:37], off offset:2048 nt
	global_load_dword v178, v[84:85], off nt
	v_lshl_add_u64 v[66:67], s[6:7], 0, v[34:35]
	s_mul_i32 s6, s8, 0x1800
	v_mad_i64_i32 v[84:85], s[70:71], s20, v195, v[82:83]
	global_load_dword v124, v[38:39], off offset:2048 nt
	global_load_dword v174, v[84:85], off nt
	s_mul_hi_i32 s5, s8, 0x1800
	s_add_u32 s6, s84, s6
	v_mad_i64_i32 v[84:85], s[70:71], s96, v195, v[82:83]
	global_load_dword v117, v[40:41], off offset:2048 nt
	global_load_dword v172, v[84:85], off nt
	s_addc_u32 s7, s85, s5
	s_or_b32 s86, s78, 31
	v_mad_i64_i32 v[84:85], s[70:71], s94, v195, v[82:83]
	global_load_dword v111, v[42:43], off offset:2048 nt
	global_load_dword v170, v[84:85], off nt
	v_lshl_add_u64 v[68:69], s[6:7], 0, v[34:35]
	s_mul_i32 s7, s86, 0x1800
	v_mad_i64_i32 v[84:85], s[70:71], s92, v195, v[82:83]
	global_load_dword v109, v[44:45], off offset:2048 nt
	global_load_dword v168, v[84:85], off nt
	s_mul_hi_i32 s5, s86, 0x1800
	s_add_u32 s68, s84, s7
	v_mad_i64_i32 v[84:85], s[70:71], s90, v195, v[82:83]
	global_load_dword v102, v[46:47], off offset:2048 nt
	global_load_dword v166, v[84:85], off nt
	s_addc_u32 s69, s85, s5
	s_min_u32 s5, s26, 0x7df
	v_mad_i64_i32 v[84:85], s[70:71], s88, v195, v[82:83]
	global_load_dword v101, v[48:49], off offset:2048 nt
	global_load_dword v164, v[84:85], off nt
	s_or_b32 s5, s5, s3
	v_mad_i64_i32 v[84:85], s[70:71], s42, v195, v[82:83]
	global_load_dword v94, v[50:51], off offset:2048 nt
	global_load_dword v162, v[84:85], off nt
	s_add_i32 s5, s5, 32
	v_mad_i64_i32 v[84:85], s[70:71], s44, v195, v[82:83]
	global_load_dword v88, v[52:53], off offset:2048 nt
	global_load_dword v160, v[84:85], off nt
	s_mul_hi_i32 s7, s5, 0x1800
	s_mulk_i32 s5, 0x1800
	v_mad_i64_i32 v[84:85], s[70:71], s30, v195, v[82:83]
	global_load_dword v86, v[54:55], off offset:2048 nt
	global_load_dword v158, v[84:85], off nt
	v_lshl_add_u64 v[70:71], s[68:69], 0, v[34:35]
	s_add_u32 s68, s84, s5
	v_mad_i64_i32 v[84:85], s[70:71], s28, v195, v[82:83]
	s_mov_b32 s6, s18
	global_load_dword v80, v[56:57], off offset:2048 nt
	global_load_dword v156, v[84:85], off nt
	s_addc_u32 s69, s85, s7
	v_mad_i64_i32 v[84:85], s[70:71], s50, v195, v[82:83]
	v_writelane_b32 v252, s6, 12
	global_load_dword v78, v[58:59], off offset:2048 nt
	global_load_dword v149, v[84:85], off nt
	v_mad_i64_i32 v[84:85], s[70:71], s48, v195, v[82:83]
	v_writelane_b32 v252, s7, 13
	s_mov_b32 s6, s16
	global_load_dword v77, v[60:61], off offset:2048 nt
	global_load_dword v148, v[84:85], off nt
	v_mad_i64_i32 v[84:85], s[70:71], s24, v195, v[82:83]
	v_writelane_b32 v252, s6, 14
	global_load_dword v76, v[62:63], off offset:2048 nt
	global_load_dword v147, v[84:85], off nt
	v_mad_i64_i32 v[84:85], s[70:71], s80, v195, v[82:83]
	v_writelane_b32 v252, s7, 15
	s_mov_b32 s6, s14
	global_load_dword v75, v[64:65], off offset:2048 nt
	global_load_dword v142, v[84:85], off nt
	v_mad_i64_i32 v[84:85], s[70:71], s40, v195, v[82:83]
	v_writelane_b32 v252, s6, 16
	global_load_dword v74, v[66:67], off offset:2048 nt
	global_load_dword v139, v[84:85], off nt
	v_mad_i64_i32 v[84:85], s[70:71], s82, v195, v[82:83]
	v_writelane_b32 v252, s7, 17
	s_mov_b32 s6, s12
	global_load_dword v73, v[68:69], off offset:2048 nt
	global_load_dword v134, v[84:85], off nt
	v_mad_i64_i32 v[84:85], s[70:71], s18, v195, v[82:83]
	v_writelane_b32 v252, s6, 18
	global_load_dword v72, v[70:71], off offset:2048 nt
	global_load_dword v131, v[84:85], off nt
	v_mad_i64_i32 v[84:85], s[70:71], s16, v195, v[82:83]
	v_writelane_b32 v252, s7, 19
	s_mov_b32 s6, s10
	global_load_dword v126, v[84:85], off nt
	v_mad_i64_i32 v[84:85], s[70:71], s14, v195, v[82:83]
	v_writelane_b32 v252, s6, 20
	global_load_dword v120, v[84:85], off nt
	v_mad_i64_i32 v[84:85], s[70:71], s12, v195, v[82:83]
	v_writelane_b32 v252, s7, 21
	s_mov_b32 s6, s4
	global_load_dword v110, v[84:85], off nt
	v_mad_i64_i32 v[84:85], s[70:71], s10, v195, v[82:83]
	v_writelane_b32 v252, s6, 22
	global_load_dword v103, v[84:85], off nt
	v_mad_i64_i32 v[84:85], s[70:71], s4, v195, v[82:83]
	v_writelane_b32 v252, s7, 23
	s_mov_b32 s4, s8
	v_writelane_b32 v252, s4, 24
	global_load_dword v95, v[84:85], off nt
	v_mad_i64_i32 v[84:85], s[70:71], s8, v195, v[82:83]
	v_writelane_b32 v252, s5, 25
	s_add_i32 s4, s26, -15
	s_max_i32 s5, s4, 0
	s_add_i32 s5, s5, s3
; template <int NT>
; __device__ __forceinline__ void even_conv_unit(const Params& p, LAS unsigned char* lds, int base, int T, int t0, int tid_in, int lane, int wave) {
;     ...
;     for (int i = 0; i < NT + 2; ++i) { const int tc = min(max(t0 - 1 + i, 0), T - 1); pv[i] = *(const unsigned*)(Z3 + (size_t)(base + tc) * ZE_LD + 1024 + 2 * tid); }
; #pragma unroll
;     for (int i = 0; i < NT; ++i) bgv[i] = *(const unsigned*)(Z3 + (size_t)(base + t0 + i) * ZE_LD + 2 * tid);
; #pragma unroll
;     for (int j = 0; j < NR; ++j) { const int tc = min(max(t0 - 15 + j, 0), T - 1); xr[j] = *(const unsigned*)(Z3 + (size_t)(base + tc) * ZE_LD + 2048 + 2 * tid); }
	v_mad_i64_i32 v[82:83], s[70:71], s86, v195, v[82:83]
	s_mul_hi_i32 s7, s5, 0x1800
	s_mulk_i32 s5, 0x1800
	s_add_u32 s70, s84, s5
	v_writelane_b32 v252, s4, 26
	s_addc_u32 s71, s85, s7
	s_add_i32 s4, s26, -14
	s_max_i32 s5, s4, 0
	s_add_i32 s5, s5, s3
	s_mul_hi_i32 s7, s5, 0x1800
	s_mulk_i32 s5, 0x1800
	global_load_dword v190, v[4:5], off offset:2048 nt
	global_load_dword v87, v[84:85], off nt
	global_load_dword v79, v[82:83], off nt
	v_lshl_add_u64 v[82:83], s[70:71], 0, v[34:35]
	s_add_u32 s70, s84, s5
	v_writelane_b32 v252, s4, 27
	s_addc_u32 s71, s85, s7
	s_add_i32 s4, s26, -13
	s_max_i32 s5, s4, 0
	v_add_co_u32_e32 v82, vcc, s75, v82
	s_add_i32 s5, s5, s3
	s_nop 0
	v_addc_co_u32_e32 v83, vcc, 0, v83, vcc
	s_mul_hi_i32 s7, s5, 0x1800
	s_mulk_i32 s5, 0x1800
	global_load_dword v198, v[6:7], off offset:2048 nt
	global_load_dword v81, v[82:83], off nt
	v_lshl_add_u64 v[82:83], s[70:71], 0, v[34:35]
	s_add_u32 s70, s84, s5
	v_writelane_b32 v252, s4, 28
	s_addc_u32 s71, s85, s7
	s_add_i32 s4, s26, -12
	s_max_i32 s5, s4, 0
	v_add_co_u32_e32 v82, vcc, s75, v82
	s_add_i32 s5, s5, s3
	s_nop 0
	v_addc_co_u32_e32 v83, vcc, 0, v83, vcc
	s_mul_hi_i32 s7, s5, 0x1800
	s_mulk_i32 s5, 0x1800
	global_load_dword v199, v[8:9], off offset:2048 nt
	global_load_dword v89, v[82:83], off nt
	v_lshl_add_u64 v[82:83], s[70:71], 0, v[34:35]
	s_add_u32 s70, s84, s5
	v_writelane_b32 v252, s4, 29
	s_addc_u32 s71, s85, s7
	s_add_i32 s4, s26, -11
	s_max_i32 s5, s4, 0
	v_add_co_u32_e32 v82, vcc, s75, v82
	s_add_i32 s5, s5, s3
	s_nop 0
	v_addc_co_u32_e32 v83, vcc, 0, v83, vcc
	s_mul_hi_i32 s7, s5, 0x1800
	s_mulk_i32 s5, 0x1800
	global_load_dword v188, v[10:11], off offset:2048 nt
	global_load_dword v100, v[82:83], off nt
	v_lshl_add_u64 v[82:83], s[70:71], 0, v[34:35]
	s_add_u32 s70, s84, s5
	v_writelane_b32 v252, s4, 30
	s_addc_u32 s71, s85, s7
	s_add_i32 s4, s26, -10
	s_max_i32 s5, s4, 0
	v_add_co_u32_e32 v82, vcc, s75, v82
	s_add_i32 s5, s5, s3
	s_nop 0
	v_addc_co_u32_e32 v83, vcc, 0, v83, vcc
	s_mul_hi_i32 s7, s5, 0x1800
	s_mulk_i32 s5, 0x1800
	global_load_dword v184, v[12:13], off offset:2048 nt
	global_load_dword v108, v[82:83], off nt
	v_lshl_add_u64 v[82:83], s[70:71], 0, v[34:35]
	s_add_u32 s70, s84, s5
	v_writelane_b32 v252, s4, 31
	s_addc_u32 s71, s85, s7
	s_add_i32 s4, s26, -9
	s_max_i32 s5, s4, 0
	v_add_co_u32_e32 v82, vcc, s75, v82
	s_add_i32 s5, s5, s3
	s_nop 0
	v_addc_co_u32_e32 v83, vcc, 0, v83, vcc
	s_mul_hi_i32 s7, s5, 0x1800
	s_mulk_i32 s5, 0x1800
	global_load_dword v176, v[14:15], off offset:2048 nt
	global_load_dword v116, v[82:83], off nt
	v_lshl_add_u64 v[82:83], s[70:71], 0, v[34:35]
	s_add_u32 s70, s84, s5
	v_writelane_b32 v252, s4, 32
	s_addc_u32 s71, s85, s7
	s_add_i32 s4, s26, -8
	s_max_i32 s5, s4, 0
	v_add_co_u32_e32 v82, vcc, s75, v82
	s_add_i32 s5, s5, s3
	s_nop 0
	v_addc_co_u32_e32 v83, vcc, 0, v83, vcc
	s_mul_hi_i32 s7, s5, 0x1800
	s_mulk_i32 s5, 0x1800
	global_load_dword v146, v[16:17], off offset:2048 nt
	global_load_dword v121, v[82:83], off nt
	v_lshl_add_u64 v[82:83], s[70:71], 0, v[34:35]
	s_add_u32 s70, s84, s5
	v_writelane_b32 v252, s4, 33
	s_addc_u32 s71, s85, s7
	s_add_i32 s4, s26, -7
	s_max_i32 s5, s4, 0
	s_add_i32 s5, s5, s3
	s_mul_hi_i32 s7, s5, 0x1800
	s_mulk_i32 s5, 0x1800
	v_lshl_add_u64 v[84:85], s[70:71], 0, v[34:35]
	s_add_u32 s70, s84, s5
	v_add_co_u32_e32 v82, vcc, s75, v82
	v_writelane_b32 v252, s4, 34
	s_addc_u32 s71, s85, s7
	s_add_i32 s4, s26, -6
	v_addc_co_u32_e32 v83, vcc, 0, v83, vcc
	s_max_i32 s5, s4, 0
	v_add_co_u32_e32 v84, vcc, s75, v84
	s_add_i32 s5, s5, s3
	s_nop 0
	v_addc_co_u32_e32 v85, vcc, 0, v85, vcc
	s_mul_hi_i32 s7, s5, 0x1800
	s_mulk_i32 s5, 0x1800
	global_load_dword v143, v[18:19], off offset:2048 nt
	v_writelane_b32 v252, s4, 35
	global_load_dword v82, v[82:83], off nt
	s_nop 0
	global_load_dword v83, v[84:85], off nt
	v_lshl_add_u64 v[84:85], s[70:71], 0, v[34:35]
	s_add_u32 s70, s84, s5
	s_addc_u32 s71, s85, s7
	s_add_i32 s4, s26, -5
	s_max_i32 s5, s4, 0
	s_add_i32 s5, s5, s3
	s_mul_hi_i32 s7, s5, 0x1800
	s_mulk_i32 s5, 0x1800
	v_lshl_add_u64 v[90:91], s[70:71], 0, v[34:35]
	s_add_u32 s70, s84, s5
	v_add_co_u32_e32 v84, vcc, s75, v84
	v_writelane_b32 v252, s4, 36
	s_addc_u32 s71, s85, s7
	s_add_i32 s4, s26, -4
	v_addc_co_u32_e32 v85, vcc, 0, v85, vcc
	s_max_i32 s5, s4, 0
	v_add_co_u32_e32 v90, vcc, s75, v90
	s_add_i32 s5, s5, s3
	s_nop 0
	v_addc_co_u32_e32 v91, vcc, 0, v91, vcc
	s_mul_hi_i32 s7, s5, 0x1800
	s_mulk_i32 s5, 0x1800
	global_load_dword v84, v[84:85], off nt
	v_writelane_b32 v252, s4, 37
	global_load_dword v85, v[90:91], off nt
	v_lshl_add_u64 v[90:91], s[70:71], 0, v[34:35]
	s_add_u32 s70, s84, s5
	s_addc_u32 s71, s85, s7
	s_add_i32 s4, s26, -3
	s_max_i32 s5, s4, 0
	s_add_i32 s5, s5, s3
	s_mul_hi_i32 s7, s5, 0x1800
	s_mulk_i32 s5, 0x1800
	v_lshl_add_u64 v[92:93], s[70:71], 0, v[34:35]
	s_add_u32 s70, s84, s5
	v_add_co_u32_e32 v90, vcc, s75, v90
	v_writelane_b32 v252, s4, 38
	s_addc_u32 s71, s85, s7
	s_add_i32 s4, s26, -2
	v_addc_co_u32_e32 v91, vcc, 0, v91, vcc
	s_max_i32 s5, s4, 0
	v_add_co_u32_e32 v92, vcc, s75, v92
	s_add_i32 s5, s5, s3
	s_nop 0
	v_addc_co_u32_e32 v93, vcc, 0, v93, vcc
	s_mul_hi_i32 s7, s5, 0x1800
	s_mulk_i32 s5, 0x1800
	global_load_dword v90, v[90:91], off nt
	v_writelane_b32 v252, s4, 39
	global_load_dword v91, v[92:93], off nt
	v_lshl_add_u64 v[92:93], s[70:71], 0, v[34:35]
	s_add_u32 s70, s84, s5
	v_add_co_u32_e32 v92, vcc, s75, v92
	s_addc_u32 s71, s85, s7
	s_nop 0
	v_addc_co_u32_e32 v93, vcc, 0, v93, vcc
	v_lshl_add_u64 v[96:97], s[70:71], 0, v[34:35]
	v_add_co_u32_e32 v96, vcc, s75, v96
	global_load_dword v92, v[92:93], off nt
	s_nop 0
; template <int NT>
; __device__ __forceinline__ void even_conv_unit(const Params& p, LAS unsigned char* lds, int base, int T, int t0, int tid_in, int lane, int wave) {
;     ...
;     for (int j = 0; j < NR; ++j) { const int tc = min(max(t0 - 15 + j, 0), T - 1); xr[j] = *(const unsigned*)(Z3 + (size_t)(base + tc) * ZE_LD + 2048 + 2 * tid); }
	v_addc_co_u32_e32 v97, vcc, 0, v97, vcc
	v_add_co_u32_e32 v4, vcc, s75, v4
	global_load_dword v93, v[96:97], off nt
	s_nop 0
	v_addc_co_u32_e32 v5, vcc, 0, v5, vcc
	global_load_dword v96, v[4:5], off nt
	v_add_co_u32_e32 v4, vcc, s75, v6
	s_min_u32 s5, s26, 0x7de
	s_nop 0
	v_addc_co_u32_e32 v5, vcc, 0, v7, vcc
	global_load_dword v97, v[4:5], off nt
	v_add_co_u32_e32 v4, vcc, s75, v8
	s_or_b32 s5, s5, s3
	s_nop 0
	v_addc_co_u32_e32 v5, vcc, 0, v9, vcc
	global_load_dword v98, v[4:5], off nt
	v_add_co_u32_e32 v4, vcc, s75, v10
	s_add_i32 s5, s5, 33
	s_nop 0
	v_addc_co_u32_e32 v5, vcc, 0, v11, vcc
	global_load_dword v104, v[4:5], off nt
	v_add_co_u32_e32 v4, vcc, s75, v12
	s_mul_hi_i32 s7, s5, 0x1800
	s_nop 0
	v_addc_co_u32_e32 v5, vcc, 0, v13, vcc
	global_load_dword v105, v[4:5], off nt
	v_add_co_u32_e32 v4, vcc, s75, v14
	s_mulk_i32 s5, 0x1800
	s_nop 0
	v_addc_co_u32_e32 v5, vcc, 0, v15, vcc
	global_load_dword v112, v[4:5], off nt
	v_add_co_u32_e32 v4, vcc, s75, v16
	s_add_u32 s70, s84, s5
	s_nop 0
	v_addc_co_u32_e32 v5, vcc, 0, v17, vcc
	global_load_dword v113, v[4:5], off nt
	v_add_co_u32_e32 v4, vcc, s75, v18
	s_addc_u32 s71, s85, s7
	s_nop 0
	v_addc_co_u32_e32 v5, vcc, 0, v19, vcc
	global_load_dword v114, v[4:5], off nt
	v_add_co_u32_e32 v4, vcc, s75, v20
	s_min_u32 s5, s26, 0x7dd
	s_nop 0
	v_addc_co_u32_e32 v5, vcc, 0, v21, vcc
	global_load_dword v118, v[4:5], off nt
	v_add_co_u32_e32 v4, vcc, s75, v22
	s_or_b32 s5, s5, s3
	s_nop 0
	v_addc_co_u32_e32 v5, vcc, 0, v23, vcc
	global_load_dword v119, v[4:5], off nt
	v_add_co_u32_e32 v4, vcc, s75, v24
	s_add_i32 s5, s5, 34
	s_nop 0
	v_addc_co_u32_e32 v5, vcc, 0, v25, vcc
	global_load_dword v127, v[4:5], off nt
	v_add_co_u32_e32 v4, vcc, s75, v26
	s_mul_hi_i32 s7, s5, 0x1800
	s_nop 0
	v_addc_co_u32_e32 v5, vcc, 0, v27, vcc
	global_load_dword v128, v[4:5], off nt
	v_add_co_u32_e32 v4, vcc, s75, v28
	s_mulk_i32 s5, 0x1800
	s_nop 0
	v_addc_co_u32_e32 v5, vcc, 0, v29, vcc
	global_load_dword v136, v[4:5], off nt
	v_add_co_u32_e32 v4, vcc, s75, v30
	s_nop 1
	v_addc_co_u32_e32 v5, vcc, 0, v31, vcc
	global_load_dword v144, v[4:5], off nt
	v_add_co_u32_e32 v4, vcc, s75, v32
	s_nop 1
	v_addc_co_u32_e32 v5, vcc, 0, v33, vcc
	global_load_dword v150, v[4:5], off nt
	v_add_co_u32_e32 v4, vcc, s75, v36
	s_nop 1
	v_addc_co_u32_e32 v5, vcc, 0, v37, vcc
	global_load_dword v152, v[4:5], off nt
	v_add_co_u32_e32 v4, vcc, s75, v38
	s_nop 1
	v_addc_co_u32_e32 v5, vcc, 0, v39, vcc
	global_load_dword v154, v[4:5], off nt
	v_add_co_u32_e32 v4, vcc, s75, v40
	s_nop 1
	v_addc_co_u32_e32 v5, vcc, 0, v41, vcc
	global_load_dword v122, v[4:5], off nt
	v_add_co_u32_e32 v4, vcc, s75, v42
	s_nop 1
	v_addc_co_u32_e32 v5, vcc, 0, v43, vcc
	global_load_dword v106, v[4:5], off nt
	v_add_co_u32_e32 v4, vcc, s75, v44
	s_nop 1
	v_addc_co_u32_e32 v5, vcc, 0, v45, vcc
	global_load_dword v99, v[4:5], off nt
	v_add_co_u32_e32 v4, vcc, s75, v46
	s_nop 1
	v_addc_co_u32_e32 v5, vcc, 0, v47, vcc
	global_load_dword v107, v[4:5], off nt
	v_add_co_u32_e32 v4, vcc, s75, v48
	s_nop 1
	v_addc_co_u32_e32 v5, vcc, 0, v49, vcc
	global_load_dword v115, v[4:5], off nt
	v_add_co_u32_e32 v4, vcc, s75, v50
	s_nop 1
	v_addc_co_u32_e32 v5, vcc, 0, v51, vcc
	global_load_dword v123, v[4:5], off nt
	v_add_co_u32_e32 v4, vcc, s75, v52
	s_nop 1
	v_addc_co_u32_e32 v5, vcc, 0, v53, vcc
	global_load_dword v129, v[4:5], off nt
	v_add_co_u32_e32 v4, vcc, s75, v54
	s_nop 1
	v_addc_co_u32_e32 v5, vcc, 0, v55, vcc
	global_load_dword v137, v[4:5], off nt
	v_add_co_u32_e32 v4, vcc, s75, v56
	s_nop 1
	v_addc_co_u32_e32 v5, vcc, 0, v57, vcc
	global_load_dword v145, v[4:5], off nt
	v_add_co_u32_e32 v4, vcc, s75, v58
	s_nop 1
	v_addc_co_u32_e32 v5, vcc, 0, v59, vcc
	global_load_dword v151, v[4:5], off nt
	v_add_co_u32_e32 v4, vcc, s75, v60
	s_nop 1
	v_addc_co_u32_e32 v5, vcc, 0, v61, vcc
	global_load_dword v153, v[4:5], off nt
	v_add_co_u32_e32 v4, vcc, s75, v62
	s_nop 1
	v_addc_co_u32_e32 v5, vcc, 0, v63, vcc
	global_load_dword v155, v[4:5], off nt
	v_add_co_u32_e32 v4, vcc, s75, v64
	s_nop 1
	v_addc_co_u32_e32 v5, vcc, 0, v65, vcc
	global_load_dword v157, v[4:5], off nt
	v_add_co_u32_e32 v4, vcc, s75, v66
	s_nop 1
	v_addc_co_u32_e32 v5, vcc, 0, v67, vcc
	global_load_dword v159, v[4:5], off nt
	v_add_co_u32_e32 v4, vcc, s75, v68
	s_nop 1
	v_addc_co_u32_e32 v5, vcc, 0, v69, vcc
	global_load_dword v161, v[4:5], off nt
	v_add_co_u32_e32 v4, vcc, s75, v70
	s_nop 1
	v_addc_co_u32_e32 v5, vcc, 0, v71, vcc
	global_load_dword v163, v[4:5], off nt
	v_lshl_add_u64 v[4:5], s[68:69], 0, v[34:35]
	v_add_co_u32_e32 v4, vcc, s75, v4
	s_nop 1
	v_addc_co_u32_e32 v5, vcc, 0, v5, vcc
	global_load_dword v165, v[4:5], off nt
	v_lshl_add_u64 v[4:5], s[70:71], 0, v[34:35]
	s_add_u32 s70, s84, s5
	s_addc_u32 s71, s85, s7
	s_min_u32 s5, s26, 0x7dc
	s_or_b32 s5, s5, s3
	v_add_co_u32_e32 v4, vcc, s75, v4
	s_add_i32 s5, s5, 35
	s_nop 0
	v_addc_co_u32_e32 v5, vcc, 0, v5, vcc
	s_mul_hi_i32 s7, s5, 0x1800
	s_mulk_i32 s5, 0x1800
	global_load_dword v167, v[4:5], off nt
	v_lshl_add_u64 v[4:5], s[70:71], 0, v[34:35]
	s_add_u32 s70, s84, s5
	s_addc_u32 s71, s85, s7
	s_min_u32 s5, s26, 0x7db
	s_or_b32 s5, s5, s3
	v_add_co_u32_e32 v4, vcc, s75, v4
	s_add_i32 s5, s5, 36
	s_nop 0
	v_addc_co_u32_e32 v5, vcc, 0, v5, vcc
	s_mul_hi_i32 s7, s5, 0x1800
	s_mulk_i32 s5, 0x1800
	global_load_dword v169, v[4:5], off nt
	v_lshl_add_u64 v[4:5], s[70:71], 0, v[34:35]
	s_add_u32 s70, s84, s5
	s_addc_u32 s71, s85, s7
	s_min_u32 s5, s26, 0x7da
	s_or_b32 s5, s5, s3
	v_add_co_u32_e32 v4, vcc, s75, v4
	s_add_i32 s5, s5, 37
	s_nop 0
	v_addc_co_u32_e32 v5, vcc, 0, v5, vcc
	s_mul_hi_i32 s7, s5, 0x1800
	s_mulk_i32 s5, 0x1800
; template <int NT>
; __device__ __forceinline__ void even_conv_unit(const Params& p, LAS unsigned char* lds, int base, int T, int t0, int tid_in, int lane, int wave) {
;     ...
;     for (int j = 0; j < NR; ++j) { const int tc = min(max(t0 - 15 + j, 0), T - 1); xr[j] = *(const unsigned*)(Z3 + (size_t)(base + tc) * ZE_LD + 2048 + 2 * tid); }
;     const f32x2 cbias = *(const f32x2*)(ccb + 2 * tid);
;     if (t0 == 0) pv[0] = 0u;
;     if (t0 + NT == T) pv[NT + 1] = 0u;
	global_load_dword v171, v[4:5], off nt
	v_lshl_add_u64 v[4:5], s[70:71], 0, v[34:35]
	s_add_u32 s70, s84, s5
	s_addc_u32 s71, s85, s7
	s_min_u32 s5, s26, 0x7d9
	s_or_b32 s5, s5, s3
	v_add_co_u32_e32 v4, vcc, s75, v4
	s_add_i32 s5, s5, 38
	s_nop 0
	v_addc_co_u32_e32 v5, vcc, 0, v5, vcc
	s_mul_hi_i32 s7, s5, 0x1800
	s_mulk_i32 s5, 0x1800
	global_load_dword v173, v[4:5], off nt
	v_lshl_add_u64 v[4:5], s[70:71], 0, v[34:35]
	s_add_u32 s70, s84, s5
	s_addc_u32 s71, s85, s7
	s_min_u32 s5, s26, 0x7d8
	s_or_b32 s5, s5, s3
	v_add_co_u32_e32 v4, vcc, s75, v4
	s_add_i32 s5, s5, 39
	s_nop 0
	v_addc_co_u32_e32 v5, vcc, 0, v5, vcc
	s_mul_hi_i32 s7, s5, 0x1800
	s_mulk_i32 s5, 0x1800
	global_load_dword v175, v[4:5], off nt
	v_lshl_add_u64 v[4:5], s[70:71], 0, v[34:35]
	s_add_u32 s70, s84, s5
	s_addc_u32 s71, s85, s7
	s_min_u32 s5, s26, 0x7d7
	s_or_b32 s5, s5, s3
	v_add_co_u32_e32 v4, vcc, s75, v4
	s_add_i32 s5, s5, 40
	s_nop 0
	v_addc_co_u32_e32 v5, vcc, 0, v5, vcc
	s_mul_hi_i32 s7, s5, 0x1800
	s_mulk_i32 s5, 0x1800
	global_load_dword v177, v[4:5], off nt
	v_lshl_add_u64 v[4:5], s[70:71], 0, v[34:35]
	s_add_u32 s70, s84, s5
	s_addc_u32 s71, s85, s7
	s_min_u32 s5, s26, 0x7d6
	s_or_b32 s5, s5, s3
	v_add_co_u32_e32 v4, vcc, s75, v4
	s_add_i32 s5, s5, 41
	s_nop 0
	v_addc_co_u32_e32 v5, vcc, 0, v5, vcc
	s_mul_hi_i32 s7, s5, 0x1800
	s_mulk_i32 s5, 0x1800
	global_load_dword v179, v[4:5], off nt
	v_lshl_add_u64 v[4:5], s[70:71], 0, v[34:35]
	s_add_u32 s70, s84, s5
	s_addc_u32 s71, s85, s7
	s_min_u32 s5, s26, 0x7d5
	s_or_b32 s5, s5, s3
	v_add_co_u32_e32 v4, vcc, s75, v4
	s_add_i32 s5, s5, 42
	s_nop 0
	v_addc_co_u32_e32 v5, vcc, 0, v5, vcc
	s_mul_hi_i32 s7, s5, 0x1800
	s_mulk_i32 s5, 0x1800
	global_load_dword v181, v[4:5], off nt
	v_lshl_add_u64 v[4:5], s[70:71], 0, v[34:35]
	s_add_u32 s70, s84, s5
	s_addc_u32 s71, s85, s7
	s_min_u32 s5, s26, 0x7d4
	s_or_b32 s5, s5, s3
	v_add_co_u32_e32 v4, vcc, s75, v4
	s_add_i32 s5, s5, 43
	s_nop 0
	v_addc_co_u32_e32 v5, vcc, 0, v5, vcc
	s_mul_hi_i32 s7, s5, 0x1800
	s_mulk_i32 s5, 0x1800
	global_load_dword v183, v[4:5], off nt
	v_lshl_add_u64 v[4:5], s[70:71], 0, v[34:35]
	s_add_u32 s70, s84, s5
	s_addc_u32 s71, s85, s7
	s_min_u32 s5, s26, 0x7d3
	s_or_b32 s5, s5, s3
	v_add_co_u32_e32 v4, vcc, s75, v4
	s_add_i32 s5, s5, 44
	s_nop 0
	v_addc_co_u32_e32 v5, vcc, 0, v5, vcc
	s_mul_hi_i32 s7, s5, 0x1800
	s_mulk_i32 s5, 0x1800
	global_load_dword v185, v[4:5], off nt
	v_lshl_add_u64 v[4:5], s[70:71], 0, v[34:35]
	s_add_u32 s70, s84, s5
	s_addc_u32 s71, s85, s7
	s_min_u32 s5, s26, 0x7d2
	s_or_b32 s5, s5, s3
	v_add_co_u32_e32 v4, vcc, s75, v4
	s_add_i32 s5, s5, 45
	s_nop 0
	v_addc_co_u32_e32 v5, vcc, 0, v5, vcc
	s_mul_hi_i32 s7, s5, 0x1800
	s_mulk_i32 s5, 0x1800
	global_load_dword v187, v[4:5], off nt
	v_lshl_add_u64 v[4:5], s[70:71], 0, v[34:35]
	s_add_u32 s70, s84, s5
	s_addc_u32 s71, s85, s7
	s_min_u32 s5, s26, 0x7d1
	v_add_co_u32_e32 v4, vcc, s75, v4
	s_or_b32 s3, s5, s3
	s_nop 0
	v_addc_co_u32_e32 v5, vcc, 0, v5, vcc
	s_add_i32 s3, s3, 46
	global_load_dword v189, v[4:5], off nt
	v_lshl_add_u64 v[4:5], s[70:71], 0, v[34:35]
	s_mul_hi_i32 s5, s3, 0x1800
	s_mulk_i32 s3, 0x1800
	v_add_co_u32_e32 v4, vcc, s75, v4
	s_add_u32 s70, s84, s3
	s_nop 0
	v_addc_co_u32_e32 v5, vcc, 0, v5, vcc
	s_addc_u32 s71, s85, s5
	global_load_dword v191, v[4:5], off nt
	v_lshl_add_u64 v[4:5], s[70:71], 0, v[34:35]
	v_add_co_u32_e32 v4, vcc, 0x1000, v4
	v_readlane_b32 s4, v253, 32
	s_nop 0
	v_addc_co_u32_e32 v5, vcc, 0, v5, vcc
	v_readlane_b32 s14, v253, 42
	v_readlane_b32 s15, v253, 43
	global_load_dword v197, v[4:5], off nt
	s_mov_b64 s[70:71], -1
	v_lshl_add_u64 v[4:5], v[2:3], 2, s[14:15]
	global_load_dwordx2 v[4:5], v[4:5], off
	s_cmpk_gt_i32 s26, 0x7df
	v_readlane_b32 s5, v253, 33
	v_readlane_b32 s6, v253, 34
	v_readlane_b32 s7, v253, 35
	v_readlane_b32 s8, v253, 36
	v_readlane_b32 s9, v253, 37
	v_readlane_b32 s10, v253, 38
	v_readlane_b32 s11, v253, 39
	v_readlane_b32 s12, v253, 40
	v_readlane_b32 s13, v253, 41
	v_readlane_b32 s16, v253, 44
	v_readlane_b32 s17, v253, 45
	v_readlane_b32 s18, v253, 46
	v_readlane_b32 s19, v253, 47
	s_cbranch_scc0 .LBB0_732
	s_mov_b64 s[70:71], 0
.LBB0_732:
	v_readlane_b32 s4, v252, 12
	v_readlane_b32 s5, v252, 13
	s_ashr_i32 s5, s4, 31
	v_writelane_b32 v252, s4, 12
	s_ashr_i32 s79, s78, 31
	s_ashr_i32 s77, s76, 31
	v_writelane_b32 v252, s5, 13
	s_ashr_i32 s35, s34, 31
	v_readlane_b32 s4, v252, 14
	v_readlane_b32 s5, v252, 15
	s_ashr_i32 s5, s4, 31
	v_writelane_b32 v252, s4, 14
	s_ashr_i32 s23, s22, 31
	s_ashr_i32 s39, s38, 31
	v_writelane_b32 v252, s5, 15
	s_ashr_i32 s37, s36, 31
	v_readlane_b32 s4, v252, 16
	v_readlane_b32 s5, v252, 17
	s_ashr_i32 s5, s4, 31
	v_writelane_b32 v252, s4, 16
	s_ashr_i32 s3, s2, 31
	s_ashr_i32 s47, s46, 31
	v_writelane_b32 v252, s5, 17
	s_ashr_i32 s21, s20, 31
	v_readlane_b32 s4, v252, 18
	v_readlane_b32 s5, v252, 19
	s_ashr_i32 s5, s4, 31
	v_writelane_b32 v252, s4, 18
	s_ashr_i32 s97, s96, 31
	s_ashr_i32 s95, s94, 31
	v_writelane_b32 v252, s5, 19
	s_ashr_i32 s93, s92, 31
	v_readlane_b32 s4, v252, 20
	v_readlane_b32 s5, v252, 21
	s_ashr_i32 s5, s4, 31
	v_writelane_b32 v252, s4, 20
	s_ashr_i32 s91, s90, 31
	s_ashr_i32 s89, s88, 31
	v_writelane_b32 v252, s5, 21
	s_ashr_i32 s43, s42, 31
	v_readlane_b32 s4, v252, 22
	v_readlane_b32 s5, v252, 23
	s_ashr_i32 s5, s4, 31
	v_writelane_b32 v252, s4, 22
	s_ashr_i32 s45, s44, 31
	s_ashr_i32 s31, s30, 31
	v_writelane_b32 v252, s5, 23
	s_ashr_i32 s29, s28, 31
	v_readlane_b32 s4, v252, 24
	v_readlane_b32 s5, v252, 25
	s_ashr_i32 s5, s4, 31
	s_ashr_i32 s51, s50, 31
	s_ashr_i32 s49, s48, 31
	s_ashr_i32 s25, s24, 31
	s_ashr_i32 s81, s80, 31
	s_ashr_i32 s41, s40, 31
	s_ashr_i32 s83, s82, 31
	v_writelane_b32 v252, s4, 24
	s_ashr_i32 s87, s86, 31
	s_andn2_b64 vcc, exec, s[70:71]
	v_mov_b32_e32 v16, 0
	v_writelane_b32 v252, s5, 25
	s_cbranch_vccnz .LBB0_735
	v_lshl_add_u64 v[6:7], v[2:3], 1, s[68:69]
	global_load_dword v16, v[6:7], off offset:2048 nt
	s_cmp_lg_u32 s26, 0
	s_cbranch_scc1 .LBB0_735
	s_waitcnt vmcnt(62)
	v_mov_b32_e32 v190, 0
